# GLA cores (retention, HGRN2): XCD-aware unit order so units sharing a q/k stream run on one XCD
# speedup vs baseline: 1.0205x; 1.0086x over previous
; #define LAS __attribute__((address_space(3)))
; template <int DK, int DVS, bool RET> ...
;     ...
;     unsigned aQD = (unsigned)(uintptr_t)(LAS unsigned char*)lds, aKD = aQD + 64 * LK * 2, aSTB = aKD + 64 * LK * 2, aVI = aSTB + DVS * LK * 2,
;              aAT = aVI + 64 * LV * 2, aEL = aAT + 64 * LS * 2, aTOT = aEL + DK * 4;
;     asm volatile("" : "+s"(aQD), "+s"(aVI), "+s"(aAT), "+s"(aEL), "+s"(aTOT), "+s"(aKD), "+s"(aSTB));
;     LAS bf16_t* QD = (LAS bf16_t*)(uintptr_t)aQD; LAS bf16_t* VI = (LAS bf16_t*)(uintptr_t)aVI; LAS bf16_t* AT = (LAS bf16_t*)(uintptr_t)aAT;
;     LAS float* EL = (LAS float*)(uintptr_t)aEL; LAS float* TOT = (LAS float*)(uintptr_t)aTOT;
;     LAS bf16_t* KD = (LAS bf16_t*)(uintptr_t)aKD; LAS bf16_t* STB = (LAS bf16_t*)(uintptr_t)aSTB;
;     static_assert(2 * 64 * LK * 2 + DVS * LK * 2 + 64 * LV * 2 + 64 * LS * 2 + DK * 4 + 2048 <= 159744, "GLA LDS map");
;     const int wid = tid >> 6, lane = tid & 63, l16 = lane & 15, quad = lane >> 4;
;     const int tr = wid >> 1, tv = wid / WPV, kt0 = (wid % WPV) * TPW;
;     const int vtr = (int)aVI + (8 * quad + (l16 >> 2)) * (LV * 2) + 8 * (lane & 3);
;     const int ktr = (int)aKD + (8 * quad + (l16 >> 2)) * (LK * 2) + 8 * (lane & 3);
;     ...
;     f32x4 st[TPW];
; #pragma unroll
;     for (int t = 0; t < TPW; ++t) st[t] = (f32x4){0.f, 0.f, 0.f, 0.f};
;     ...
;     typedef short vvec_t __attribute__((ext_vector_type(VPT)));
;     constexpr int NQV = RET ? 4 : 1, NLC = RET ? 1 : PPT;
;     bf16x8 qv[NQV], kv[NQV]; float lc[NLC]; bf16_t qr[NLC]; vvec_t vraw;
;     const int kx = tid % DK, pg = tid / DK;
; __global__ void __launch_bounds__(512) mk_fwd(Params P) {
;     ...
;             for (int L = bid; L < 256; L += G) {
;                 const int slice = L & 3, dir = (L >> 2) & 1, hh = (L >> 3) & 7, bq = L >> 6;
.LBB0_48:
	s_andn2_b64 vcc, exec, s[14:15]
	s_cbranch_vccnz .LBB0_59
	s_cmpk_gt_i32 s2, 0xff
	s_cbranch_scc1 .LBB0_59
	v_ashrrev_i32_e32 v2, 6, v146
	s_waitcnt lgkmcnt(0)
	v_lshrrev_b32_e32 v1, 30, v2
	v_add_u32_e32 v1, v2, v1
	v_bfe_u32 v0, v146, 4, 2
	v_ashrrev_i32_e32 v3, 2, v1
	v_and_b32_e32 v1, -4, v1
	s_waitcnt vmcnt(0)
	v_sub_u32_e32 v4, v2, v1
	v_lshlrev_b32_e32 v9, 3, v0
	v_bfe_u32 v1, v146, 2, 2
	v_or_b32_e32 v5, v9, v1
	v_lshlrev_b32_e32 v1, 3, v146
	v_and_b32_e32 v1, 24, v1
	s_movk_i32 s6, 0x50
	v_mad_u32_u24 v76, v5, s6, v1
	v_ashrrev_i32_e32 v1, 31, v146
	v_lshrrev_b32_e32 v1, 25, v1
	v_lshlrev_b32_e32 v7, 2, v0
	v_lshlrev_b32_e32 v0, 2, v146
	v_add_u32_e32 v1, v146, v1
	v_and_b32_e32 v0, 28, v0
	v_ashrrev_i32_e32 v6, 7, v1
	v_and_b32_e32 v1, 0xffffff80, v1
	v_lshlrev_b32_e32 v14, 1, v0
	v_mov_b32_e32 v15, v145
	v_sub_u32_e32 v10, v146, v1
	v_lshl_add_u64 v[0:1], s[0:1], 0, v[14:15]
	s_mov_b64 s[6:7], 0xbf69000
	v_ashrrev_i32_e32 v93, 3, v146
	v_lshl_add_u64 v[16:17], v[0:1], 0, s[6:7]
	v_add_u32_e32 v0, 0x7f, v146
	v_ashrrev_i32_e32 v11, 31, v10
	v_cmp_gt_u32_e32 vcc, s43, v0
	v_and_b32_e32 v0, 1, v2
	v_bfi_b32 v2, -16, v93, v146
	s_movk_i32 s7, 0x110
	s_movk_i32 s16, 0x90
	s_movk_i32 s14, 0x880
	v_lshlrev_b32_e32 v77, 4, v6
	v_lshl_or_b32 v18, v3, 4, v7
	v_mul_lo_u32 v94, v2, s7
	v_mul_lo_u32 v99, v2, s16
	v_lshlrev_b32_e32 v100, 5, v3
	v_mad_u64_u32 v[2:3], s[14:15], v6, s14, v[10:11]
	v_and_b32_e32 v8, 15, v146
	v_or_b32_e32 v78, 1, v77
	v_lshlrev_b32_e32 v15, 5, v0
	v_and_b32_e32 v1, -16, v93
	v_lshlrev_b32_e32 v0, 4, v0
	s_movk_i32 s14, 0x88
	v_or_b32_e32 v95, v15, v8
	v_or_b32_e32 v97, v7, v1
	v_or_b32_e32 v7, v0, v8
	s_movk_i32 s6, 0xc0
	v_mul_lo_u32 v103, v18, s7
	v_mad_u64_u32 v[18:19], s[14:15], v78, s14, v[10:11]
	s_add_u32 s3, s0, 0x10369000
	v_or_b32_e32 v1, 16, v95
	v_mul_u32_u24_e32 v98, 0x110, v7
	v_mad_u32_u24 v101, v5, s6, v76
	v_lshl_or_b32 v5, v4, 1, 1
	s_movk_i32 s6, 0x7f
	s_movk_i32 s10, 0x17f
	s_movk_i32 s12, 0x1ff
	v_add_u32_e32 v3, 0x88, v18
	v_add_u32_e32 v6, 0x110, v18
	v_add_u32_e32 v7, 0x198, v18
	v_add_u32_e32 v20, 0x220, v18
	v_add_u32_e32 v21, 0x2a8, v18
	v_add_u32_e32 v22, 0x330, v18
	v_add_u32_e32 v23, 0x3b8, v18
	v_add_u32_e32 v24, 0x440, v18
	v_add_u32_e32 v25, 0x4c8, v18
	v_add_u32_e32 v26, 0x550, v18
	v_add_u32_e32 v27, 0x5d8, v18
	v_add_u32_e32 v28, 0x660, v18
	v_add_u32_e32 v29, 0x6e8, v18
	v_add_u32_e32 v30, 0x770, v18
	v_mul_lo_u32 v19, v97, s16
	v_or_b32_e32 v105, 1, v97
	v_or_b32_e32 v107, 2, v97
	v_or_b32_e32 v109, 3, v97
	s_mov_b64 s[70:71], s[86:87]
	s_addc_u32 s48, s1, 0
	v_lshl_add_u64 v[12:13], v[10:11], 1, s[90:91]
	v_or_b32_e32 v79, 2, v77
	v_or_b32_e32 v80, 3, v77
	v_or_b32_e32 v81, 4, v77
	v_or_b32_e32 v82, 5, v77
	v_or_b32_e32 v83, 6, v77
	v_or_b32_e32 v84, 7, v77
	v_or_b32_e32 v85, 8, v77
	v_or_b32_e32 v86, 9, v77
	v_or_b32_e32 v87, 10, v77
	v_or_b32_e32 v88, 11, v77
	v_or_b32_e32 v89, 12, v77
	v_or_b32_e32 v90, 13, v77
	v_or_b32_e32 v91, 14, v77
	v_or_b32_e32 v92, 15, v77
	v_mul_u32_u24_e32 v96, 0x110, v95
	v_lshlrev_b32_e32 v102, 6, v4
	v_lshlrev_b32_e32 v104, 5, v5
	v_cmp_lt_i32_e64 s[6:7], s6, v146
	v_cmp_lt_i32_e64 s[8:9], s43, v146
	v_cmp_lt_i32_e64 s[10:11], s10, v146
	v_cmp_lt_i32_e64 s[12:13], s12, v146
	v_cmp_gt_i32_e64 s[14:15], v95, v97
	v_cmp_gt_i32_e64 s[16:17], v1, v97
	v_cmp_gt_i32_e64 s[18:19], v95, v105
	v_add_u32_e32 v106, 0x90, v19
	v_cmp_gt_i32_e64 s[20:21], v1, v105
	v_cmp_gt_i32_e64 s[22:23], v95, v107
	v_add_u32_e32 v108, 0x120, v19
	v_cmp_gt_i32_e64 s[24:25], v1, v107
	v_cmp_gt_i32_e64 s[26:27], v95, v109
	v_add_u32_e32 v250, 0x1b0, v19
	v_cmp_gt_i32_e64 s[28:29], v1, v109
	v_sub_u32_e32 v251, 63, v97
	v_sub_u32_e32 v252, 63, v105
	v_sub_u32_e32 v198, 63, v107
	v_sub_u32_e32 v114, 63, v109
	v_lshlrev_b32_e32 v115, 7, v4
	v_lshlrev_b32_e32 v116, 6, v5
	v_lshlrev_b32_e32 v144, 1, v0
	v_lshlrev_b32_e32 v117, 1, v2
	v_lshlrev_b32_e32 v118, 1, v3
	v_lshlrev_b32_e32 v119, 1, v6
	v_lshlrev_b32_e32 v120, 1, v7
	v_lshlrev_b32_e32 v121, 1, v20
	v_lshlrev_b32_e32 v122, 1, v21
	v_lshlrev_b32_e32 v123, 1, v22
	v_lshlrev_b32_e32 v124, 1, v23
	v_lshlrev_b32_e32 v125, 1, v24
	v_lshlrev_b32_e32 v126, 1, v25
	v_lshlrev_b32_e32 v127, 1, v26
	v_lshlrev_b32_e32 v128, 1, v27
	v_lshlrev_b32_e32 v129, 1, v28
	v_lshlrev_b32_e32 v130, 1, v29
	v_lshlrev_b32_e32 v131, 1, v30
	s_mov_b32 s49, s2
	s_cmp_lg_u32 s80, 0x100
	s_cbranch_scc1 .Lhg_noperm
	s_and_b32 s49, s2, 7
	s_lshl_b32 s49, s49, 5
	s_lshr_b32 s36, s2, 3
	s_or_b32 s49, s49, s36
.Lhg_noperm:
	s_branch .LBB0_52
.LBB0_51:
	s_add_i32 s49, s49, s80
	s_cmpk_gt_i32 s49, 0xff
	s_barrier
	s_cbranch_scc1 .LBB0_58

; #define LAS __attribute__((address_space(3)))
; template <int DK, int DVS, bool RET> ...
;     ...
;     unsigned aQD = (unsigned)(uintptr_t)(LAS unsigned char*)lds, aKD = aQD + 64 * LK * 2, aSTB = aKD + 64 * LK * 2, aVI = aSTB + DVS * LK * 2,
;              aAT = aVI + 64 * LV * 2, aEL = aAT + 64 * LS * 2, aTOT = aEL + DK * 4;
;     asm volatile("" : "+s"(aQD), "+s"(aVI), "+s"(aAT), "+s"(aEL), "+s"(aTOT), "+s"(aKD), "+s"(aSTB));
;     LAS bf16_t* QD = (LAS bf16_t*)(uintptr_t)aQD; LAS bf16_t* VI = (LAS bf16_t*)(uintptr_t)aVI; LAS bf16_t* AT = (LAS bf16_t*)(uintptr_t)aAT;
;     LAS float* EL = (LAS float*)(uintptr_t)aEL; LAS float* TOT = (LAS float*)(uintptr_t)aTOT;
;     LAS bf16_t* KD = (LAS bf16_t*)(uintptr_t)aKD; LAS bf16_t* STB = (LAS bf16_t*)(uintptr_t)aSTB;
;     static_assert(2 * 64 * LK * 2 + DVS * LK * 2 + 64 * LV * 2 + 64 * LS * 2 + DK * 4 + 2048 <= 159744, "GLA LDS map");
;     const int wid = tid >> 6, lane = tid & 63, l16 = lane & 15, quad = lane >> 4;
;     const int tr = wid >> 1, tv = wid / WPV, kt0 = (wid % WPV) * TPW;
;     const int vtr = (int)aVI + (8 * quad + (l16 >> 2)) * (LV * 2) + 8 * (lane & 3);
;     const int ktr = (int)aKD + (8 * quad + (l16 >> 2)) * (LK * 2) + 8 * (lane & 3);
;     ...
;     f32x4 st[TPW];
; #pragma unroll
;     for (int t = 0; t < TPW; ++t) st[t] = (f32x4){0.f, 0.f, 0.f, 0.f};
;     ...
;     typedef short vvec_t __attribute__((ext_vector_type(VPT)));
;     constexpr int NQV = RET ? 4 : 1, NLC = RET ? 1 : PPT;
;     bf16x8 qv[NQV], kv[NQV]; float lc[NLC]; bf16_t qr[NLC]; vvec_t vraw;
;     const int kx = tid % DK, pg = tid / DK;
; __global__ void __launch_bounds__(512) mk_fwd(Params P) {
;     ...
;             for (int L = bid; L < 256; L += G) {
;                 const int slice = L & 7, dir = (L >> 3) & 1, hh = (L >> 4) & 3, bq = L >> 6;
.LBB0_65:
	s_andn2_b64 vcc, exec, s[14:15]
	s_cbranch_vccnz .LBB0_76
	s_cmpk_gt_i32 s2, 0xff
	s_cbranch_scc1 .LBB0_76
	s_waitcnt vmcnt(0)
	v_add_u32_e32 v7, 0x200, v146
	v_ashrrev_i32_e32 v7, 3, v7
	v_and_b32_e32 v72, -8, v7
	v_add_u32_e32 v7, 0x400, v146
	v_ashrrev_i32_e32 v7, 3, v7
	v_ashrrev_i32_e32 v2, 6, v146
	s_waitcnt lgkmcnt(0)
	v_lshrrev_b32_e32 v1, 31, v146
	v_and_b32_e32 v74, -8, v7
	v_add_u32_e32 v7, 0x600, v146
	v_add_u32_e32 v1, v2, v1
	v_ashrrev_i32_e32 v7, 3, v7
	v_bfe_u32 v0, v146, 4, 2
	v_ashrrev_i32_e32 v3, 1, v1
	v_and_b32_e32 v1, -2, v1
	v_and_b32_e32 v76, -8, v7
	v_ashrrev_i32_e32 v7, 31, v146
	v_sub_u32_e32 v4, v2, v1
	v_lshlrev_b32_e32 v69, 3, v0
	v_bfe_u32 v1, v146, 2, 2
	v_add_u32_sdwa v7, v146, v7 dst_sel:DWORD dst_unused:UNUSED_PAD src0_sel:DWORD src1_sel:BYTE_3
	v_or_b32_e32 v5, v69, v1
	v_lshlrev_b32_e32 v1, 3, v146
	v_and_b32_e32 v7, 0xffffff00, v7
	v_sub_u32_e32 v118, v146, v7
	v_lshlrev_b32_e32 v7, 2, v0
	v_and_b32_e32 v0, 56, v1
	v_lshlrev_b32_e32 v78, 1, v0
	v_mov_b32_e32 v79, v145
	v_and_b32_e32 v6, 24, v1
	v_lshl_add_u64 v[0:1], s[0:1], 0, v[78:79]
	s_mov_b64 s[6:7], 0xe169000
	v_lshl_add_u64 v[80:81], v[0:1], 0, s[6:7]
	v_add_u32_e32 v0, 1, v148
	v_cvt_f32_ubyte0_e32 v79, v0
	v_add_u32_e32 v0, 0xff, v146
	s_movk_i32 s3, 0x1ff
	v_cmp_gt_u32_e32 vcc, s3, v0
	v_lshlrev_b32_e32 v0, 1, v2
	v_ashrrev_i32_e32 v117, 3, v146
	v_and_b32_e32 v2, 2, v0
	v_and_b32_e32 v68, 15, v146
	s_movk_i32 s8, 0x90
	v_lshl_or_b32 v8, v3, 4, v7
	v_and_b32_e32 v9, -16, v117
	v_lshlrev_b32_e32 v0, 4, v2
	v_lshlrev_b32_e32 v126, 5, v3
	v_or_b32_e32 v3, 1, v2
	v_mad_u32_u24 v116, v5, s8, v6
	v_lshlrev_b32_e32 v6, 3, v4
	v_bfi_b32 v10, -16, v117, v146
	s_movk_i32 s6, 0x210
	v_or_b32_e32 v122, v0, v68
	v_or_b32_e32 v124, v7, v9
	s_movk_i32 s3, 0x180
	s_waitcnt vmcnt(0)
	v_lshlrev_b32_e32 v151, 5, v2
	v_lshlrev_b32_e32 v2, 4, v3
	s_add_u32 s26, s0, 0xbf69000
	v_and_b32_e32 v70, -8, v117
	v_mul_u32_u24_e32 v1, 0x108, v148
	v_mul_lo_u32 v121, v10, s6
	v_or_b32_e32 v7, 16, v122
	v_mul_lo_u32 v125, v10, s8
	v_mad_u32_u24 v127, v5, s3, v116
	v_lshlrev_b32_e32 v128, 5, v3
	v_lshlrev_b32_e32 v129, 8, v4
	v_mul_lo_u32 v130, v8, s6
	v_or_b32_e32 v5, 1, v6
	v_or_b32_e32 v8, 2, v6
	v_or_b32_e32 v9, 3, v6
	v_or_b32_e32 v10, 4, v6
	v_or_b32_e32 v11, 5, v6
	v_or_b32_e32 v12, 6, v6
	v_or_b32_e32 v6, 7, v6
	v_mul_lo_u32 v138, v124, s8
	v_or_b32_e32 v139, 1, v124
	v_or_b32_e32 v141, 2, v124
	v_or_b32_e32 v143, 3, v124
	v_or_b32_e32 v3, v2, v68
	s_addc_u32 s27, s1, 0
	v_ashrrev_i32_e32 v71, 31, v70
	v_ashrrev_i32_e32 v73, 31, v72
	v_ashrrev_i32_e32 v75, 31, v74
	v_ashrrev_i32_e32 v77, 31, v76
	v_sub_u32_e32 v119, 63, v117
	v_mul_lo_u32 v120, v117, s8
	v_mul_u32_u24_e32 v123, 0x210, v122
	v_lshlrev_b32_e32 v131, 5, v5
	v_lshlrev_b32_e32 v132, 5, v8
	v_lshlrev_b32_e32 v133, 5, v9
	v_lshlrev_b32_e32 v134, 5, v10
	v_lshlrev_b32_e32 v135, 5, v11
	v_lshlrev_b32_e32 v136, 5, v12
	v_lshlrev_b32_e32 v137, 5, v6
	v_cmp_gt_i32_e64 s[6:7], v122, v124
	v_cmp_gt_i32_e64 s[8:9], v7, v124
	v_cmp_gt_i32_e64 s[10:11], v122, v139
	v_add_u32_e32 v140, 0x90, v138
	v_cmp_gt_i32_e64 s[12:13], v7, v139
	v_cmp_gt_i32_e64 s[14:15], v122, v141
	v_add_u32_e32 v142, 0x120, v138
	v_cmp_gt_i32_e64 s[16:17], v7, v141
	v_cmp_gt_i32_e64 s[18:19], v122, v143
	v_add_u32_e32 v147, 0x1b0, v138
	v_cmp_gt_i32_e64 s[20:21], v7, v143
	v_sub_u32_e32 v150, 63, v124
	v_sub_u32_e32 v152, 63, v139
	v_sub_u32_e32 v153, 63, v141
	v_sub_u32_e32 v154, 63, v143
	v_mul_u32_u24_e32 v155, 0x210, v3
	v_or_b32_e32 v156, 64, v129
	v_or_b32_e32 v157, 0x60, v129
	v_or_b32_e32 v158, 0x80, v129
	v_or_b32_e32 v159, 0xa0, v129
	v_or_b32_e32 v160, 0xc0, v129
	v_or_b32_e32 v161, 0xe0, v129
	v_lshlrev_b32_e32 v162, 9, v4
	v_lshlrev_b32_e32 v163, 6, v5
	v_lshlrev_b32_e32 v164, 6, v8
	v_lshlrev_b32_e32 v165, 6, v9
	v_lshlrev_b32_e32 v166, 6, v10
	v_lshlrev_b32_e32 v167, 6, v11
	v_lshlrev_b32_e32 v168, 6, v12
	v_lshlrev_b32_e32 v169, 6, v6
	v_lshlrev_b32_e32 v170, 1, v1
	v_lshlrev_b32_e32 v82, 1, v0
	v_lshlrev_b32_e32 v84, 1, v2
	s_mov_b32 s3, s2
	s_cmp_lg_u32 s80, 0x100
	s_cbranch_scc1 .Lret_noperm
	s_and_b32 s3, s2, 7
	s_lshl_b32 s3, s3, 5
	s_lshr_b32 s28, s2, 3
	s_or_b32 s3, s3, s28
.Lret_noperm:
	s_branch .LBB0_69
.LBB0_68:
	s_add_i32 s3, s3, s80
	s_cmpk_gt_i32 s3, 0xff
	s_mov_b32 s47, 0x16969000
	s_barrier
	s_cbranch_scc1 .LBB0_75
